# grid barrier: non-leader workgroups poll the cross-XCD release word directly and issue their L1 invalidate before the release poll (on top of dattn loop + GEMM setprio/barrier reorder)
# speedup vs baseline: 1.0128x; 1.0116x over previous
.LBB0_129:
	s_or_b64 exec, exec, s[8:9]
	v_cvt_f32_u32_e32 v4, v2
	s_waitcnt vmcnt(0)
	v_readfirstlane_b32 s3, v3
	v_sub_u32_e32 v3, 0, v2
	v_rcp_iflag_f32_e32 v4, v4
	v_add_u32_e32 v5, s3, v1
	v_mul_f32_e32 v4, 0x4f7ffffe, v4
	v_cvt_u32_f32_e32 v4, v4
	v_mul_lo_u32 v1, v3, v4
	v_mul_hi_u32 v1, v4, v1
	v_add_u32_e32 v1, v4, v1
	v_mul_hi_u32 v1, v5, v1
	v_mul_lo_u32 v3, v1, v2
	v_sub_u32_e32 v3, v5, v3
	v_add_u32_e32 v4, 1, v1
	v_cmp_ge_u32_e32 vcc, v3, v2
	s_nop 1
	v_cndmask_b32_e32 v1, v1, v4, vcc
	v_sub_u32_e32 v4, v3, v2
	v_cndmask_b32_e32 v3, v3, v4, vcc
	v_add_u32_e32 v4, 1, v1
	v_cmp_ge_u32_e32 vcc, v3, v2
	v_add_u32_e32 v3, 1, v5
	s_nop 0
	v_cndmask_b32_e32 v1, v1, v4, vcc
	v_mul_lo_u32 v4, v2, v1
	v_add_u32_e32 v2, v4, v2
	v_cmp_ne_u32_e32 vcc, v3, v2
	s_and_saveexec_b64 s[6:7], vcc
	s_xor_b64 s[6:7], exec, s[6:7]
	s_cbranch_execz .LBB0_143
	s_waitcnt lgkmcnt(0)
	buffer_inv sc1
	v_mov_b32_e32 v0, 0x7500
	global_load_dword v0, v0, s[74:75] sc1
	s_add_u32 s12, s74, 0x7500
	s_addc_u32 s13, s75, 0
	s_waitcnt vmcnt(0)
	v_cmp_eq_u32_e32 vcc, v0, v1
	s_and_saveexec_b64 s[8:9], vcc
	s_cbranch_execz .LBB0_142
	s_add_u32 s10, s74, 0x4200
	s_addc_u32 s11, s75, 0
	s_mov_b32 s3, 1
	s_mov_b64 s[14:15], 0
	v_mov_b32_e32 v0, 0
	s_branch .LBB0_133

.LBB0_142:
	s_or_b64 exec, exec, s[8:9]
	s_waitcnt vmcnt(0)
	s_waitcnt vmcnt(0)

.LBB0_642:
	s_or_b64 exec, exec, s[10:11]
	v_cvt_f32_u32_e32 v4, v2
	s_waitcnt vmcnt(0)
	v_readfirstlane_b32 s3, v3
	v_sub_u32_e32 v3, 0, v2
	v_rcp_iflag_f32_e32 v4, v4
	v_add_u32_e32 v5, s3, v1
	v_mul_f32_e32 v4, 0x4f7ffffe, v4
	v_cvt_u32_f32_e32 v4, v4
	v_mul_lo_u32 v1, v3, v4
	v_mul_hi_u32 v1, v4, v1
	v_add_u32_e32 v1, v4, v1
	v_mul_hi_u32 v1, v5, v1
	v_mul_lo_u32 v3, v1, v2
	v_sub_u32_e32 v3, v5, v3
	v_add_u32_e32 v4, 1, v1
	v_cmp_ge_u32_e32 vcc, v3, v2
	s_nop 1
	v_cndmask_b32_e32 v1, v1, v4, vcc
	v_sub_u32_e32 v4, v3, v2
	v_cndmask_b32_e32 v3, v3, v4, vcc
	v_add_u32_e32 v4, 1, v1
	v_cmp_ge_u32_e32 vcc, v3, v2
	v_add_u32_e32 v3, 1, v5
	s_nop 0
	v_cndmask_b32_e32 v1, v1, v4, vcc
	v_mul_lo_u32 v4, v2, v1
	v_add_u32_e32 v2, v4, v2
	v_cmp_ne_u32_e32 vcc, v3, v2
	s_and_saveexec_b64 s[8:9], vcc
	s_xor_b64 s[8:9], exec, s[8:9]
	s_cbranch_execz .LBB0_656
	s_waitcnt lgkmcnt(0)
	buffer_inv sc1
	v_mov_b32_e32 v0, 0x7500
	global_load_dword v0, v0, s[74:75] sc1
	s_add_u32 s14, s74, 0x7500
	s_addc_u32 s15, s75, 0
	s_waitcnt vmcnt(0)
	v_cmp_eq_u32_e32 vcc, v0, v1
	s_and_saveexec_b64 s[10:11], vcc
	s_cbranch_execz .LBB0_655
	s_add_u32 s12, s74, 0x4200
	s_addc_u32 s13, s75, 0
	s_mov_b32 s3, 1
	s_mov_b64 s[16:17], 0
	v_mov_b32_e32 v0, 0
	s_branch .LBB0_646

.LBB0_655:
	s_or_b64 exec, exec, s[10:11]
	s_waitcnt vmcnt(0)
	s_waitcnt vmcnt(0)

.LBB0_1430:
	s_or_b64 exec, exec, s[12:13]
	v_cvt_f32_u32_e32 v4, v2
	s_waitcnt vmcnt(0)
	v_readfirstlane_b32 s2, v3
	v_sub_u32_e32 v3, 0, v2
	v_rcp_iflag_f32_e32 v4, v4
	v_add_u32_e32 v5, s2, v1
	v_mul_f32_e32 v4, 0x4f7ffffe, v4
	v_cvt_u32_f32_e32 v4, v4
	v_mul_lo_u32 v1, v3, v4
	v_mul_hi_u32 v1, v4, v1
	v_add_u32_e32 v1, v4, v1
	v_mul_hi_u32 v1, v5, v1
	v_mul_lo_u32 v3, v1, v2
	v_sub_u32_e32 v3, v5, v3
	v_add_u32_e32 v4, 1, v1
	v_cmp_ge_u32_e32 vcc, v3, v2
	s_nop 1
	v_cndmask_b32_e32 v1, v1, v4, vcc
	v_sub_u32_e32 v4, v3, v2
	v_cndmask_b32_e32 v3, v3, v4, vcc
	v_add_u32_e32 v4, 1, v1
	v_cmp_ge_u32_e32 vcc, v3, v2
	v_add_u32_e32 v3, 1, v5
	s_nop 0
	v_cndmask_b32_e32 v1, v1, v4, vcc
	v_mul_lo_u32 v4, v2, v1
	v_add_u32_e32 v2, v4, v2
	v_cmp_ne_u32_e32 vcc, v3, v2
	s_and_saveexec_b64 s[2:3], vcc
	s_xor_b64 s[10:11], exec, s[2:3]
	s_cbranch_execz .LBB0_1444
	s_waitcnt lgkmcnt(0)
	buffer_inv sc1
	v_mov_b32_e32 v0, 0x7500
	global_load_dword v0, v0, s[74:75] sc1
	s_add_u32 s16, s74, 0x7500
	s_addc_u32 s17, s75, 0
	s_waitcnt vmcnt(0)
	v_cmp_eq_u32_e32 vcc, v0, v1
	s_and_saveexec_b64 s[12:13], vcc
	s_cbranch_execz .LBB0_1443
	s_add_u32 s14, s74, 0x4200
	s_addc_u32 s15, s75, 0
	s_mov_b32 s2, 1
	s_mov_b64 s[18:19], 0
	v_mov_b32_e32 v0, 0
	s_branch .LBB0_1434

.LBB0_1443:
	s_or_b64 exec, exec, s[12:13]
	s_waitcnt vmcnt(0)
	s_waitcnt vmcnt(0)
